# work-queue steal polls: one coherent 8-counter peek at the first steal attempt; queues already exhausted are skipped without an atomic round trip (stacked on the unit-prologue load batching)
# speedup vs baseline: 1.0135x; 1.0016x over previous
.LBB0_232:
	s_add_i32 s0, s16, s52
	s_and_b32 s0, s0, 7
	s_lshl_b32 s1, s0, 8
	v_readlane_b32 s2, v253, 60
	v_readlane_b32 s3, v253, 61
	s_add_u32 s48, s2, s1
	s_addc_u32 s49, s3, 0
	s_and_saveexec_b64 s[4:5], s[34:35]
	s_cbranch_execz .LBB0_236
	s_mov_b64 s[8:9], exec
	v_mbcnt_lo_u32_b32 v0, s8, 0
	v_mbcnt_hi_u32_b32 v0, s9, v0
	v_cmp_eq_u32_e32 vcc, 0, v0
	s_and_saveexec_b64 s[6:7], vcc
	s_cbranch_execz .LBB0_235
	s_cmp_lg_u32 s16, 1
	s_cbranch_scc1 .Lpk_use_0
	v_readlane_b32 s100, v253, 60
	v_readlane_b32 s101, v253, 61
	s_mov_b64 exec, 0xff
	v_mbcnt_lo_u32_b32 v2, -1, 0
	v_lshlrev_b32_e32 v2, 8, v2
	s_nop 3
	global_load_dword v2, v2, s[100:101] sc1
	s_waitcnt vmcnt(0)
	v_cmp_lt_u32_e32 vcc, 0x7f, v2
	s_nop 1
	s_mov_b32 s98, vcc_lo
	s_mov_b64 exec, 1
.Lpk_use_0:
	s_cmp_eq_u32 s16, 0
	s_cbranch_scc1 .Lpk_atom_0
	s_bitcmp1_b32 s98, s0
	s_cbranch_scc0 .Lpk_atom_0
	v_mov_b32_e32 v2, 0x80
	s_branch .LBB0_235
.Lpk_atom_0:
	s_bcnt1_i32_b64 s1, s[8:9]
	v_mov_b32_e32 v2, s1
	global_atomic_add v2, v1, v2, s[48:49] sc0

.LBB0_313:
	s_add_i32 s2, s0, s52
	s_and_b32 s2, s2, 7
	s_lshl_b32 s3, s2, 8
	v_readlane_b32 s4, v253, 60
	v_readlane_b32 s5, v253, 61
	s_add_u32 s4, s4, s3
	s_addc_u32 s5, s5, 0
	s_and_saveexec_b64 s[6:7], s[34:35]
	s_cbranch_execz .LBB0_317
	s_mov_b64 s[10:11], exec
	v_mbcnt_lo_u32_b32 v0, s10, 0
	v_mbcnt_hi_u32_b32 v0, s11, v0
	v_cmp_eq_u32_e32 vcc, 0, v0
	s_and_saveexec_b64 s[8:9], vcc
	s_cbranch_execz .LBB0_316
	s_cmp_lg_u32 s0, 1
	s_cbranch_scc1 .Lpk_use_1
	v_readlane_b32 s100, v253, 60
	v_readlane_b32 s101, v253, 61
	s_mov_b64 exec, 0xff
	v_mbcnt_lo_u32_b32 v2, -1, 0
	v_lshlrev_b32_e32 v2, 8, v2
	s_nop 3
	global_load_dword v2, v2, s[100:101] offset:2048 sc1
	s_waitcnt vmcnt(0)
	v_cmp_lt_u32_e32 vcc, 0x7f, v2
	s_nop 1
	s_mov_b32 s98, vcc_lo
	s_mov_b64 exec, 1
.Lpk_use_1:
	s_cmp_eq_u32 s0, 0
	s_cbranch_scc1 .Lpk_atom_1
	s_bitcmp1_b32 s98, s2
	s_cbranch_scc0 .Lpk_atom_1
	v_mov_b32_e32 v2, 0x80
	s_branch .LBB0_316
.Lpk_atom_1:
	s_bcnt1_i32_b64 s3, s[10:11]
	v_mov_b32_e32 v2, s3
	global_atomic_add v2, v1, v2, s[4:5] offset:2048 sc0

; __device__ __forceinline__ float bflo(unsigned w) { return __uint_as_float(w << 16); }
; __device__ __forceinline__ float bfhi(unsigned w) { return __uint_as_float(w & 0xffff0000u); }
; __device__ __forceinline__ float xhalf_sum(float v) { auto rr = __builtin_amdgcn_permlane32_swap(__float_as_uint(v), __float_as_uint(v), false, false); return __uint_as_float(rr[0]) + __uint_as_float(rr[1]); }
; template <int MODE> ...
;     ...
;     { const bf16* qp = QK + (tok0 + wq0 + r32) * N1A + qcol + hi * 8;
; #pragma unroll
;       for (int d0 = 0; d0 < 4; ++d0) qr[d0] = *(const bf16x8*)(qp + d0 * 16); }
;     float qkb = 0.f;
;     if (REV) {
; #pragma unroll
;         for (int d0 = 0; d0 < 4; ++d0) { const u32x4 w = __builtin_bit_cast(u32x4, qr[d0]);
;             qkb += fabsf(pg8::bflo(w.x)) + fabsf(pg8::bfhi(w.x)) + fabsf(pg8::bflo(w.y)) + fabsf(pg8::bfhi(w.y)) + fabsf(pg8::bflo(w.z)) + fabsf(pg8::bfhi(w.z)) + fabsf(pg8::bflo(w.w)) + fabsf(pg8::bfhi(w.w)); }
;         qkb = xhalf_sum(qkb) * kinf * 1.02f;
;     }
;     const int t_lo = MODE == 1 ? (q0 >= 128 ? (q0 - 128) / 64 : 0) : 0, t_hi = (q0 + ROWS) / 64;
;     int kgoff[NKL], kloff[NKL], vgoff[NVL], vloff[NVL];
; #pragma unroll
;     for (int i = 0; i < NKL; ++i) { const int idx = tid + 512 * i, row = idx / KCH, ch = idx % KCH; kgoff[i] = row * N1A + ch * 8; kloff[i] = row * KSTR + ch * 16; }
; #pragma unroll
;     for (int i = 0; i < NVL; ++i) { const int idx = tid + 512 * i, row = idx >> 3, ch = idx & 7; vgoff[i] = row * M + ch * 8; vloff[i] = row * VSTR + ch * 16; }
;     u32x4 kstA[NKL], vstA[NVL], kstB[NKL], vstB[NVL]; float lfA = 0.f, lfB = 0.f, carry = 0.f;
; __device__ __forceinline__ void attn_phase(LAS unsigned char* lds, const Args& a, int layer, int vcu, int G) {
;     ...
;     ATT_QUEUE(1, 128, { const int s = 15 - (int)(u >> 3), h = (int)(u & 7u);
;         int l15_ = threadIdx.x & 15; asm volatile("" : "+v"(l15_)); float kinf = kabs[(b * 16 + l15_) * 11 + 8 + (h >> 2)];
;         _Pragma("unroll") for (int o = 1; o < 16; o <<= 1) kinf = fmaxf(kinf, __shfl_xor(kinf, o));
;         attn_unit<2>(lds, QK, VT, Y, logf, b, h, s, 0.f, 0.f, 0.f, 0.f, subg, kinf); });
.LBB0_324:
	s_or_b64 exec, exec, s[6:7]
	v_mov_b32_e32 v0, v197
	s_bfe_u32 s2, s13, 0x10002
	v_add_u32_e32 v0, s26, v0
	v_mul_lo_u32 v0, v0, 11
	v_add3_u32 v2, v0, s2, 8
	v_ashrrev_i32_e32 v3, 31, v2
	v_lshl_add_u64 v[2:3], v[2:3], 2, s[88:89]
	global_load_dword v10, v[2:3], off
	v_mov_b32_e32 v8, v196
	s_not_b32 s6, s13
	v_readfirstlane_b32 s2, v8
	s_ashr_i32 s15, s2, 6
	s_lshl_b32 s6, s6, 5
	s_and_b32 s12, s13, 7
	s_and_b32 s13, s6, 0xf00
	s_lshl_b32 s16, s15, 5
	s_add_i32 s84, s16, s13
	s_lshl_b32 s10, s12, 7
	s_add_u32 s8, s71, s10
	s_addc_u32 s9, s75, 0
	s_lshl_b32 s14, s12, 22
	s_add_u32 s18, s82, s14
	s_addc_u32 s19, s83, 0
	s_ashr_i32 s6, s84, 31
	v_and_b32_e32 v132, 31, v8
	s_add_u32 s77, s84, s70
	v_or_b32_e32 v0, s77, v132
	v_mov_b64_e32 v[2:3], s[80:81]
	s_addc_u32 s76, s6, 0
	v_mad_u64_u32 v[2:3], s[6:7], v0, s30, v[2:3]
	v_mov_b32_e32 v0, 0x1600
	v_bfe_u32 v7, v8, 5, 1
	s_mov_b32 s11, s69
	v_mad_i32_i24 v3, s76, v0, v3
	v_lshl_add_u64 v[4:5], v[2:3], 0, s[10:11]
	v_lshlrev_b32_e32 v2, 4, v7
	v_mov_b32_e32 v3, v1
	v_lshl_add_u64 v[4:5], v[4:5], 0, v[2:3]
	global_load_dwordx4 v[66:69], v[4:5], off offset:3072
	global_load_dwordx4 v[70:73], v[4:5], off offset:3104
	global_load_dwordx4 v[74:77], v[4:5], off offset:3136
	global_load_dwordx4 v[78:81], v[4:5], off offset:3168
	v_ashrrev_i32_e32 v0, 31, v8
	v_lshrrev_b32_e32 v0, 29, v0
	v_add_u32_e32 v11, v8, v0
	v_ashrrev_i32_e32 v12, 3, v11
	v_and_b32_e32 v4, 0xffffff8, v11
	s_movk_i32 s6, 0x90
	v_sub_u32_e32 v4, v8, v4
	v_mul_lo_u32 v5, v12, s6
	v_and_b32_e32 v3, 63, v8
	v_ashrrev_i32_e32 v9, 3, v8
	v_lshlrev_b32_e32 v6, 4, v8
	v_lshl_add_u32 v8, v4, 4, v5
	v_mad_u64_u32 v[4:5], s[6:7], v12, s73, v[8:9]
	s_add_u32 s11, s8, 0x1000
	s_addc_u32 s17, s9, 0
	s_add_i32 s6, s13, 0x100
	s_lshl_b32 s7, s70, 1
	s_add_u32 s7, s18, s7
	s_addc_u32 s8, s19, 0
	s_add_u32 s18, s7, 0x2000000
	s_addc_u32 s19, s8, 0
	s_lshr_b32 s85, s6, 6
	s_add_i32 s68, s85, -1
	s_mul_i32 s6, s68, 0x58000
	s_mul_hi_u32 s7, s68, 0x58000
	s_add_u32 s6, s11, s6
	s_addc_u32 s7, s17, s7
	s_lshl_b64 s[8:9], s[68:69], 7
	v_and_b32_e32 v6, 0x70, v6
	s_add_u32 s8, s18, s8
	v_lshl_or_b32 v0, v9, 16, v6
	s_addc_u32 s9, s19, s9
	global_load_dwordx4 v[82:85], v4, s[6:7]
	global_load_dwordx4 v[86:89], v0, s[8:9]
	s_waitcnt vmcnt(39)
	v_mov_b32_e32 v133, 0
	s_cmp_gt_u32 s2, 63
	s_cbranch_scc1 .Lfox_nolf
	s_lshl_b32 s99, s68, 6
	s_add_i32 s99, s99, s70
	v_or_b32_e32 v90, s99, v3
	v_mov_b32_e32 v91, v1
	v_readlane_b32 s100, v253, 62
	v_lshlrev_b64 v[90:91], 5, v[90:91]
	v_readlane_b32 s101, v253, 63
	s_nop 1
	v_lshl_add_u64 v[90:91], s[100:101], 0, v[90:91]
	s_lshl_b32 s100, s12, 2
	s_mov_b32 s101, 0
	v_lshl_add_u64 v[90:91], v[90:91], 0, s[100:101]
	global_load_dword v133, v[90:91], off

.LBB0_392:
	s_add_i32 s2, s3, s52
	s_and_b32 s2, s2, 7
	s_lshl_b32 s4, s2, 8
	v_readlane_b32 s6, v253, 60
	v_readlane_b32 s7, v253, 61
	s_add_u32 s4, s6, s4
	s_addc_u32 s5, s7, 0
	s_add_u32 s42, s4, 0x1000
	s_addc_u32 s43, s5, 0
	s_and_saveexec_b64 s[4:5], s[34:35]
	s_cbranch_execz .LBB0_396
	s_mov_b64 s[8:9], exec
	v_mbcnt_lo_u32_b32 v0, s8, 0
	v_mbcnt_hi_u32_b32 v0, s9, v0
	v_cmp_eq_u32_e32 vcc, 0, v0
	s_and_saveexec_b64 s[6:7], vcc
	s_cbranch_execz .LBB0_395
	s_cmp_lg_u32 s3, 1
	s_cbranch_scc1 .Lpk_use_2
	v_readlane_b32 s100, v253, 60
	v_readlane_b32 s101, v253, 61
	s_nop 0
	s_add_u32 s100, s100, 0x1000
	s_addc_u32 s101, s101, 0
	s_mov_b64 exec, 0xff
	v_mbcnt_lo_u32_b32 v2, -1, 0
	v_lshlrev_b32_e32 v2, 8, v2
	s_nop 3
	global_load_dword v2, v2, s[100:101] sc1
	s_waitcnt vmcnt(0)
	v_cmp_lt_u32_e32 vcc, 0x7f, v2
	s_nop 1
	s_mov_b32 s98, vcc_lo
	s_mov_b64 exec, 1
.Lpk_use_2:
	s_cmp_eq_u32 s3, 0
	s_cbranch_scc1 .Lpk_atom_2
	s_bitcmp1_b32 s98, s2
	s_cbranch_scc0 .Lpk_atom_2
	v_mov_b32_e32 v2, 0x80
	s_branch .LBB0_395
.Lpk_atom_2:
	s_bcnt1_i32_b64 s8, s[8:9]
	v_mov_b32_e32 v2, s8
	global_atomic_add v2, v1, v2, s[42:43] sc0
